# attention loop: one static s_setprio 1 for waves 4-7, reset at loop exit
# baseline (speedup 1.0000x reference)
; __device__ __forceinline__ void attn_phase(LAS unsigned char* lds, int vcu, int G, const bf16* Qp, const bf16* Kp, const bf16* Vt, const float* sinks, bf16* AO, int ldo, float* st) {
;     ...
;     const int lane = tid & 63, wave = __builtin_amdgcn_readfirstlane(tid >> 6), r32 = lane & 31, hi = lane >> 5, hq = wave & 3, qsub = wave >> 2;
;     const float NEG = -INFINITY;
;     float ssq_acc = 0.f;
;     for (int it = 0; it < 4; ++it) { const int id = ((vcu >> 5) << 7) | (it << 5) | (vcu & 31);
;         const int b = id >> 7, kvh = (id >> 5) & 3, q0 = 64 * (id & 31), h = kvh * 4 + hq;
;         const size_t tok0 = (size_t)b * SEQ;
;         const int jt0 = (q0 >= 128) ? 0 : (128 - q0) / 32;
;         v4u kv[3], vv[3];
; #pragma unroll
;         for (int i = 0; i < 3; ++i) { const int c = tid + 512 * i, row = c >> 3, ch = c & 7, key = q0 - 128 + row;
;             if (key >= 0) kv[i] = *(const v4u*)(Kp + (tok0 + key) * D_KV + kvh * HD + ch * 8); }
; #pragma unroll
;         for (int i = 0; i < 3; ++i) { const int c = tid + 512 * i, d = c / 24, ch = c - d * 24, key0 = q0 - 128 + 8 * ch;
;             if (key0 >= 0) vv[i] = *(const v4u*)(Vt + (size_t)(kvh * HD + d) * M + tok0 + key0); }
;         const bf16* qrow = Qp + (tok0 + q0 + 32 * qsub + r32) * D_ATTN + h * HD + 32 * hi;
.LBB0_654:
	v_writelane_b32 v254, s88, 53
	v_mov_b32_e32 v4, v0
	s_mov_b32 s15, 0x2aaaaaab
	v_writelane_b32 v254, s89, 54
	v_writelane_b32 v254, s2, 55
	v_readfirstlane_b32 s68, v4
	s_lshr_b32 s0, s68, 6
	v_writelane_b32 v254, s3, 56
	v_writelane_b32 v254, s0, 57
	s_lshl_b32 s0, s90, 6
	v_mul_hi_i32 v9, v4, s15
	s_bfe_i32 s66, s90, 0x190005
	s_and_b32 s3, s0, 0x7c0
	v_add_u32_e32 v8, 0x200, v4
	v_lshrrev_b32_e32 v13, 31, v9
	v_ashrrev_i32_e32 v9, 2, v9
	s_ashr_i32 s67, s66, 31
	v_mov_b32_e32 v3, s3
	s_sub_i32 s0, 0x80, s3
	v_add_u32_e32 v16, v9, v13
	v_mul_hi_i32 v9, v8, s15
	s_ashr_i32 s2, s68, 8
	s_lshl_b64 s[62:63], s[66:67], 11
	v_sub_co_u32_e32 v3, vcc, 0x7f, v3
	s_lshr_b32 s4, s0, 5
	v_lshrrev_b32_e32 v13, 31, v9
	v_ashrrev_i32_e32 v9, 2, v9
	s_and_b64 s[0:1], vcc, exec
	s_movk_i32 s16, 0xffe8
	v_add_u32_e32 v22, v9, v13
	s_cselect_b32 s28, 0, s4
	v_ashrrev_i32_e32 v25, 3, v8
	v_mad_u64_u32 v[8:9], s[4:5], v22, s16, v[8:9]
	s_add_i32 s14, s3, 0xffffff80
	v_lshlrev_b32_e32 v9, 3, v8
	v_add_u32_e32 v12, 0x400, v4
	v_add_u32_e32 v13, s14, v9
	v_cmp_lt_i32_e64 s[12:13], -1, v13
	v_mul_hi_i32 v13, v12, s15
	v_bfe_u32 v141, v4, 5, 1
	v_lshlrev_b32_e32 v5, 4, v4
	v_lshrrev_b32_e32 v24, 31, v13
	v_ashrrev_i32_e32 v13, 2, v13
	s_lshl_b32 s76, s2, 5
	v_and_b32_e32 v26, 0x70, v5
	v_lshlrev_b32_e32 v5, 2, v141
	v_add_u32_e32 v24, v13, v24
	s_ashr_i32 s77, s76, 31
	v_ashrrev_i32_e32 v30, 3, v12
	v_mad_u64_u32 v[18:19], s[4:5], v16, s16, v[4:5]
	v_mad_u64_u32 v[12:13], s[4:5], v24, s16, v[12:13]
	v_ashrrev_i32_e32 v23, 3, v4
	v_lshlrev_b32_e32 v19, 3, v18
	v_lshlrev_b32_e32 v13, 3, v12
	s_movk_i32 s5, 0x188
	s_cmp_ge_i32 s2, s28
	v_add_u32_e32 v20, s14, v19
	v_cmp_gt_i32_e64 s[16:17], v23, v3
	v_cmp_gt_i32_e64 s[18:19], v25, v3
	v_cmp_gt_i32_e64 s[20:21], v30, v3
	v_cmp_gt_i32_e64 s[22:23], v19, v3
	v_mul_lo_u32 v19, v16, s5
	v_cmp_gt_i32_e64 s[24:25], v9, v3
	v_mul_lo_u32 v9, v22, s5
	v_cmp_gt_i32_e64 s[26:27], v13, v3
	v_mul_lo_u32 v3, v24, s5
	s_cselect_b64 s[82:83], -1, 0
	s_add_i32 s5, s2, 1
	s_cmp_ge_i32 s5, s28
	v_and_b32_e32 v140, 31, v4
	s_cselect_b64 s[72:73], -1, 0
	s_add_i32 s60, s2, 2
	s_movk_i32 s4, 0x90
	v_lshlrev_b32_e32 v34, 4, v8
	v_or_b32_e32 v8, s76, v140
	s_cmp_ge_i32 s60, s28
	v_mul_lo_u32 v36, v8, s4
	v_lshl_or_b32 v8, s5, 5, v140
	s_cselect_b64 s[88:89], -1, 0
	s_add_i32 s69, s2, 3
	v_mul_lo_u32 v37, v8, s4
	v_lshl_or_b32 v8, s60, 5, v140
	s_cmp_ge_i32 s69, s28
	v_mul_lo_u32 v38, v8, s4
	s_cselect_b64 s[96:97], -1, 0
	v_lshl_or_b32 v8, s69, 5, v140
	s_add_i32 s70, s2, 4
	v_mul_lo_u32 v39, v8, s4
	v_lshl_or_b32 v8, s70, 5, v140
	v_mul_lo_u32 v40, v8, s4
	v_or_b32_e32 v8, 2, v5
	v_cmp_gt_u32_e64 s[34:35], v8, v140
	v_or_b32_e32 v8, 3, v5
	v_cmp_gt_u32_e64 s[36:37], v8, v140
	v_or_b32_e32 v8, 8, v5
	v_cmp_gt_u32_e64 s[38:39], v8, v140
	v_or_b32_e32 v8, 9, v5
	v_cmp_gt_u32_e64 s[40:41], v8, v140
	v_or_b32_e32 v8, 10, v5
	v_cmp_gt_u32_e64 s[42:43], v8, v140
	v_or_b32_e32 v8, 11, v5
	v_cmp_gt_u32_e64 s[44:45], v8, v140
	v_or_b32_e32 v8, 16, v5
	v_cmp_gt_u32_e64 s[46:47], v8, v140
	v_or_b32_e32 v8, 17, v5
	v_cmp_gt_u32_e64 s[48:49], v8, v140
	v_or_b32_e32 v8, 18, v5
	v_lshlrev_b32_e32 v28, 6, v141
	v_cmp_gt_u32_e64 s[50:51], v8, v140
	v_or_b32_e32 v8, 19, v5
	v_add_u32_e32 v29, 0, v28
	s_movk_i32 s0, 0xffc8
	v_cmp_gt_u32_e64 s[52:53], v8, v140
	v_or_b32_e32 v8, 24, v5
	v_mad_i32_i24 v17, v141, s0, v29
	v_add_u32_e32 v31, s14, v13
	v_cmp_gt_u32_e64 s[54:55], v8, v140
	v_or_b32_e32 v8, 25, v5
	v_add_u32_e32 v6, s14, v23
	v_add_u32_e32 v10, s14, v25
	v_add_u32_e32 v14, s14, v30
	v_cmp_lt_i32_e64 s[14:15], -1, v31
	v_mul_lo_u32 v31, v23, s4
	v_mul_lo_u32 v32, v25, s4
	s_cmp_ge_i32 s70, s28
	v_cmp_gt_u32_e64 s[56:57], v8, v140
	v_or_b32_e32 v8, 26, v5
	v_lshl_add_u32 v41, s5, 6, v17
	v_lshl_add_u32 v42, s60, 6, v17
	v_lshl_add_u32 v43, s2, 6, v17
	v_lshl_add_u32 v45, s69, 6, v17
	v_lshl_add_u32 v46, s70, 6, v17
	v_ashrrev_i32_e32 v17, 31, v16
	v_ashrrev_i32_e32 v23, 31, v22
	v_ashrrev_i32_e32 v25, 31, v24
	v_mul_lo_u32 v30, v30, s4
	v_add_u32_e32 v33, 0, v9
	v_lshlrev_b32_e32 v35, 4, v12
	s_cselect_b64 s[74:75], -1, 0
	v_cmp_gt_u32_e64 s[58:59], v8, v140
	v_lshlrev_b64 v[8:9], 15, v[16:17]
	s_lshl_b64 s[4:5], s[66:67], 12
	v_lshlrev_b64 v[12:13], 15, v[22:23]
	v_lshlrev_b64 v[16:17], 15, v[24:25]
	v_mov_b32_e32 v21, v2
	v_cmp_gt_u32_e64 s[28:29], v5, v140
	v_cmp_lt_u32_e64 s[30:31], v5, v140
; __device__ __forceinline__ void attn_phase(LAS unsigned char* lds, int vcu, int G, const bf16* Qp, const bf16* Kp, const bf16* Vt, const float* sinks, bf16* AO, int ldo, float* st) {
;     ...
;         v4u kv[3], vv[3];
; #pragma unroll
;         for (int i = 0; i < 3; ++i) { const int c = tid + 512 * i, row = c >> 3, ch = c & 7, key = q0 - 128 + row;
;             if (key >= 0) kv[i] = *(const v4u*)(Kp + (tok0 + key) * D_KV + kvh * HD + ch * 8); }
; #pragma unroll
;         for (int i = 0; i < 3; ++i) { const int c = tid + 512 * i, d = c / 24, ch = c - d * 24, key0 = q0 - 128 + 8 * ch;
;             if (key0 >= 0) vv[i] = *(const v4u*)(Vt + (size_t)(kvh * HD + d) * M + tok0 + key0); }
;         const bf16* qrow = Qp + (tok0 + q0 + 32 * qsub + r32) * D_ATTN + h * HD + 32 * hi;
;         bf16x8 qf[4];
; #pragma unroll
;         for (int kk = 0; kk < 4; ++kk) qf[kk] = *(const bf16x8*)(qrow + 8 * kk);
	v_or_b32_e32 v5, 27, v5
	v_lshl_add_u64 v[8:9], v[8:9], 0, s[4:5]
	v_lshl_add_u64 v[12:13], v[12:13], 0, s[4:5]
	v_lshl_add_u64 v[16:17], v[16:17], 0, s[4:5]
	s_movk_i32 s4, 0xc0
	v_cmp_lt_i32_e64 s[10:11], -1, v20
	v_cmp_gt_u32_e64 s[60:61], v5, v140
	v_lshl_add_u64 v[8:9], v[20:21], 1, v[8:9]
	v_mul_lo_u32 v5, v22, s4
	v_mul_lo_u32 v20, v24, s4
	s_mov_b64 s[4:5], 0xd800000
	v_lshl_add_u64 v[124:125], v[8:9], 0, s[4:5]
	v_lshl_add_u32 v8, v4, 3, s3
	v_sub_u32_e32 v4, v8, v5
	v_add_u32_e32 v4, 0xf80, v4
	v_mov_b32_e32 v5, v2
	v_lshl_add_u64 v[4:5], v[4:5], 1, v[12:13]
	v_lshl_add_u64 v[126:127], v[4:5], 0, s[4:5]
	v_sub_u32_e32 v4, v8, v20
	v_add_u32_e32 v4, 0x1f80, v4
	v_mov_b32_e32 v5, v2
	v_mov_b32_e32 v7, v2
	v_lshl_add_u64 v[4:5], v[4:5], 1, v[16:17]
	v_lshl_add_u64 v[128:129], v[4:5], 0, s[4:5]
	s_lshl_b64 s[4:5], s[66:67], 20
	v_lshlrev_b64 v[4:5], 9, v[6:7]
	v_lshl_add_u64 v[4:5], s[4:5], 0, v[4:5]
	v_mov_b32_e32 v11, v2
	v_or_b32_e32 v4, v4, v26
	s_mov_b64 s[66:67], 0xd000000
	v_lshl_add_u64 v[130:131], v[4:5], 0, s[66:67]
	v_lshlrev_b64 v[4:5], 9, v[10:11]
	v_lshl_add_u64 v[4:5], s[4:5], 0, v[4:5]
	v_mov_b32_e32 v15, v2
	v_or_b32_e32 v4, v4, v26
	v_lshl_add_u64 v[132:133], v[4:5], 0, s[66:67]
	v_lshlrev_b64 v[4:5], 9, v[14:15]
	v_lshl_add_u64 v[4:5], s[4:5], 0, v[4:5]
	s_lshr_b32 s4, s68, 4
	s_and_b32 s4, s4, 12
	s_add_u32 s4, s64, s4
	s_addc_u32 s5, s65, 0
	v_writelane_b32 v254, s90, 58
	v_or_b32_e32 v4, v4, v26
	s_add_u32 s62, s62, s76
	v_lshl_add_u64 v[134:135], v[4:5], 0, s[66:67]
	v_writelane_b32 v254, s76, 59
	s_addc_u32 s63, s63, s77
	v_or_b32_e32 v4, s3, v140
	v_mov_b32_e32 v5, v2
	v_lshl_add_u64 v[4:5], s[62:63], 0, v[4:5]
	s_lshl_b32 s62, s68, 1
	v_cmp_lt_i32_e64 s[0:1], -1, v6
	v_lshlrev_b64 v[6:7], 12, v[4:5]
	s_and_b32 s64, s62, 0x180
	v_lshlrev_b32_e32 v8, 3, v141
	v_or3_b32 v6, v6, s64, v8
	s_mov_b64 s[62:63], 0xf000040
	v_lshlrev_b64 v[4:5], 11, v[4:5]
	v_lshl_add_u64 v[136:137], v[6:7], 0, s[62:63]
	v_or3_b32 v4, v4, s64, v28
	s_mov_b64 s[62:63], 0xb000020
	v_add_u32_e32 v27, 0, v26
	v_add_u32_e32 v19, 0, v19
	v_lshlrev_b32_e32 v18, 4, v18
	v_add_u32_e32 v3, 0, v3
	v_mul_u32_u24_e32 v44, 0x188, v140
	v_writelane_b32 v254, s77, 60
	v_lshl_add_u64 v[138:139], v[4:5], 0, s[62:63]
	s_movk_i32 s62, 0x6c00
	v_cmp_lt_i32_e64 s[6:7], -1, v10
	v_cmp_lt_i32_e64 s[8:9], -1, v14
	v_writelane_b32 v254, s3, 61
	s_mov_b64 s[76:77], 0
	v_add_u32_e32 v142, v27, v31
	v_add_u32_e32 v143, v27, v32
	v_add_u32_e32 v144, v27, v30
	v_add3_u32 v145, v19, v18, s62
	v_add3_u32 v146, v33, v34, s62
	v_add3_u32 v147, v3, v35, s62
	v_add_u32_e32 v148, v29, v36
	v_add_u32_e32 v149, v29, v37
	v_add_u32_e32 v150, v29, v38
	v_add_u32_e32 v151, v29, v39
	v_add_u32_e32 v152, v29, v40
	v_mbcnt_hi_u32_b32 v1, -1, v1
	v_add_u32_e32 v153, v43, v44
	v_add_u32_e32 v154, v41, v44
	v_add_u32_e32 v155, v42, v44
	v_add_u32_e32 v156, v45, v44
	v_add_u32_e32 v157, v46, v44
	s_mov_b64 s[78:79], 0x200000
	s_mov_b64 s[90:91], 0x80
	v_mov_b32_e32 v158, 0xff800000
	v_mov_b32_e32 v159, 0
	s_mov_b32 s3, 0x3fb8aa3b
	v_readfirstlane_b32 vcc_lo, v0
	s_nop 3
	s_lshr_b32 vcc_lo, vcc_lo, 6
	s_cmp_ge_u32 vcc_lo, 4
	s_cbranch_scc0 .Lattn_prio_done
	s_setprio 1
.Lattn_prio_done:
	s_mov_b64 exec, s[0:1]
	v_lshl_add_u64 v[240:241], s[94:95], 0, v[130:131]
	global_load_dwordx4 v[200:203], v[240:241], off
	s_mov_b64 exec, s[6:7]
	v_lshl_add_u64 v[240:241], s[94:95], 0, v[132:133]
	global_load_dwordx4 v[204:207], v[240:241], off
	s_mov_b64 exec, s[8:9]
	v_lshl_add_u64 v[240:241], s[94:95], 0, v[134:135]
	global_load_dwordx4 v[208:211], v[240:241], off
	s_mov_b64 exec, s[10:11]
	v_lshl_add_u64 v[240:241], s[94:95], 0, v[124:125]
	global_load_dwordx4 v[212:215], v[240:241], off
	s_mov_b64 exec, s[12:13]
	v_lshl_add_u64 v[240:241], s[94:95], 0, v[126:127]
	global_load_dwordx4 v[216:219], v[240:241], off
	s_mov_b64 exec, s[14:15]
	v_lshl_add_u64 v[240:241], s[94:95], 0, v[128:129]
	global_load_dwordx4 v[220:223], v[240:241], off
	s_mov_b64 exec, -1
	v_lshl_add_u64 v[240:241], s[94:95], 0, v[138:139]
	global_load_dwordx4 v[224:227], v[240:241], off offset:-32
	global_load_dwordx4 v[228:231], v[240:241], off offset:-16
	global_load_dwordx4 v[232:235], v[240:241], off
	global_load_dwordx4 v[236:239], v[240:241], off offset:16
	s_add_u32 vcc_lo, s4, s76
	s_addc_u32 vcc_hi, s5, s77
	global_load_dword v242, v2, vcc
	s_waitcnt vmcnt(0)
	s_branch .LBB0_656

; #define LAS __attribute__((address_space(3)))
; __device__ __forceinline__ void attn_phase(LAS unsigned char* lds, int vcu, int G, const bf16* Qp, const bf16* Kp, const bf16* Vt, const float* sinks, bf16* AO, int ldo, float* st) {
;     ...
;     {
;         LAS float* Xs = (LAS float*)lds;
;         if (hi == 0) Xs[(qsub * 4 + hq) * 32 + r32] = ssq_acc;
.LBB0_700:
	s_setprio 0
	v_readlane_b32 s0, v254, 57
	s_and_b32 s4, s0, 3
	v_cmp_eq_u32_e32 vcc, 0, v141
	s_and_saveexec_b64 s[0:1], vcc
	s_cbranch_execz .LBB0_702
	s_lshl_b32 s3, s2, 9
	s_add_i32 s3, s3, 0
	s_lshl_b32 s5, s4, 7
	s_add_i32 s3, s3, s5
	v_lshl_add_u32 v2, v140, 2, s3
	ds_write_b32 v2, v159
